# v89 + p34_plain_safe: P3 merged / P4 xmb+SSQ stored write-back and read from the producer XCD's L2; placement verified at run time (per bid%8 class a single XCC id), full write-back fallback otherwise
# speedup vs baseline: 1.0086x; 1.0086x over previous
.LBB0_2:
	s_or_b64 exec, exec, s[4:5]
	s_load_dwordx16 s[40:55], s[0:1], 0x0
	s_waitcnt lgkmcnt(0)
	s_barrier
	s_add_u32 s88, s80, 0x2380000
	s_getreg_b32 s4, hwreg(HW_REG_XCC_ID, 0, 4)
	s_addc_u32 s89, s81, 0
	s_and_b32 s87, s4, 15
	s_and_saveexec_b64 s[4:5], s[94:95]
	s_cbranch_execz .LBB0_5
	s_mov_b64 s[6:7], exec
	v_mbcnt_lo_u32_b32 v1, s6, 0
	v_mbcnt_hi_u32_b32 v1, s7, v1
	v_cmp_eq_u32_e32 vcc, 0, v1
	s_and_b64 s[8:9], exec, vcc
	s_mov_b64 exec, s[8:9]
	s_cbranch_execz .LBB0_5
	s_lshl_b32 s8, s87, 8
	s_bcnt1_i32_b64 s6, s[6:7]
	v_mov_b32_e32 v1, s8
	v_mov_b32_e32 v2, s6
	global_atomic_add v1, v2, s[88:89] offset:1024
	s_and_b32 s9, s2, 7
	s_lshl_b32 s9, s9, 2
	s_add_i32 s9, s9, 0x100
	s_add_i32 s8, s87, 1
	v_mov_b32_e32 v3, s9
	v_mov_b32_e32 v4, s8
	s_sub_i32 s8, 16, s87
	v_mov_b32_e32 v5, s8
	global_atomic_umax v3, v4, s[88:89]
	global_atomic_umax v3, v5, s[88:89] offset:64

.Lxb_done_0:
	s_waitcnt vmcnt(0)
	s_mov_b64 exec, 0xff
	v_mbcnt_lo_u32_b32 v4, -1, 0
	v_lshlrev_b32_e32 v4, 2, v4
	v_add_u32_e32 v4, 0x100, v4
	global_load_dword v6, v4, s[6:7] sc1
	global_load_dword v5, v4, s[6:7] offset:64 sc1
	s_waitcnt vmcnt(0)
	v_add_u32_e32 v6, v6, v5
	v_cmp_ne_u32_e32 vcc, 17, v6
	s_nop 3
	s_cmp_lg_u64 vcc, 0
	s_cselect_b32 s32, 1, 0
	s_cmp_lg_u32 s3, 0x100
	s_cselect_b32 s8, 1, 0
	s_or_b32 s32, s32, s8
	s_mov_b64 exec, 1

.LBB0_408:
	s_add_i32 s4, s62, 0x200
	s_ashr_i32 s5, s4, 31
	s_lshl_b64 s[4:5], s[4:5], 16
	v_lshl_add_u64 v[2:3], v[208:209], 0, s[4:5]
	global_load_dwordx4 v[132:135], v[2:3], off
	global_load_dwordx4 v[136:139], v[2:3], off offset:1024
	v_pk_mul_f32 v[140:141], v[106:107], s[16:17] op_sel_hi:[1,0]
	v_pk_mul_f32 v[142:143], v[104:105], s[16:17] op_sel_hi:[1,0]
	global_load_dwordx4 v[104:107], v[2:3], off offset:2048
	v_pk_mul_f32 v[144:145], v[102:103], s[16:17] op_sel_hi:[1,0]
	v_pk_mul_f32 v[146:147], v[100:101], s[16:17] op_sel_hi:[1,0]
	global_load_dwordx4 v[100:103], v[2:3], off offset:3072
	s_lshl_b32 s4, s59, 9
	s_lshl_b32 s5, s28, 19
	v_pk_mul_f32 v[130:131], v[130:131], s[16:17] op_sel_hi:[1,0]
	v_pk_mul_f32 v[128:129], v[128:129], s[16:17] op_sel_hi:[1,0]
	v_pk_mul_f32 v[126:127], v[126:127], s[16:17] op_sel_hi:[1,0]
	v_pk_mul_f32 v[124:125], v[124:125], s[16:17] op_sel_hi:[1,0]
	v_pk_mul_f32 v[122:123], v[122:123], s[16:17] op_sel_hi:[1,0]
	v_pk_mul_f32 v[120:121], v[120:121], s[16:17] op_sel_hi:[1,0]
	v_pk_mul_f32 v[118:119], v[118:119], s[16:17] op_sel_hi:[1,0]
	v_pk_mul_f32 v[116:117], v[116:117], s[16:17] op_sel_hi:[1,0]
	v_pk_mul_f32 v[114:115], v[114:115], s[16:17] op_sel_hi:[1,0]
	v_pk_mul_f32 v[112:113], v[112:113], s[16:17] op_sel_hi:[1,0]
	v_pk_mul_f32 v[110:111], v[110:111], s[16:17] op_sel_hi:[1,0]
	v_pk_mul_f32 v[108:109], v[108:109], s[16:17] op_sel_hi:[1,0]
	s_add_i32 s5, s5, s4
	v_add_u32_e32 v0, s5, v218
	v_add_u32_e32 v170, 0x8000, v0
	v_pk_mul_f32 v[96:97], v[96:97], s[16:17] op_sel_hi:[1,0]
	v_pk_mul_f32 v[98:99], v[98:99], s[16:17] op_sel_hi:[1,0]
	v_pk_mul_f32 v[88:89], v[88:89], s[16:17] op_sel_hi:[1,0]
	v_pk_mul_f32 v[90:91], v[90:91], s[16:17] op_sel_hi:[1,0]
	v_pk_mul_f32 v[80:81], v[80:81], s[16:17] op_sel_hi:[1,0]
	v_pk_mul_f32 v[82:83], v[82:83], s[16:17] op_sel_hi:[1,0]
	v_pk_mul_f32 v[72:73], v[72:73], s[16:17] op_sel_hi:[1,0]
	v_pk_mul_f32 v[74:75], v[74:75], s[16:17] op_sel_hi:[1,0]
	v_add_co_u32_e32 v2, vcc, s57, v2
	v_pk_mul_f32 v[64:65], v[64:65], s[16:17] op_sel_hi:[1,0]
	s_nop 0
	v_addc_co_u32_e32 v3, vcc, 0, v3, vcc
	global_load_dwordx4 v[224:227], v[2:3], off
	global_load_dwordx4 v[228:231], v[2:3], off offset:1024
	global_load_dwordx4 v[232:235], v[2:3], off offset:2048
	global_load_dwordx4 v[236:239], v[2:3], off offset:3072
	v_pk_mul_f32 v[56:57], v[56:57], s[16:17] op_sel_hi:[1,0]
	v_pk_mul_f32 v[48:49], v[48:49], s[16:17] op_sel_hi:[1,0]
	v_pk_mul_f32 v[40:41], v[40:41], s[16:17] op_sel_hi:[1,0]
	v_pk_mul_f32 v[32:33], v[32:33], s[16:17] op_sel_hi:[1,0]
	v_pk_mul_f32 v[24:25], v[24:25], s[16:17] op_sel_hi:[1,0]
	v_pk_mul_f32 v[16:17], v[16:17], s[16:17] op_sel_hi:[1,0]
	v_pk_mul_f32 v[10:11], v[10:11], s[16:17] op_sel_hi:[1,0]
	v_pk_mul_f32 v[4:5], v[4:5], s[16:17] op_sel_hi:[1,0]
	v_pk_mul_f32 v[6:7], v[6:7], s[16:17] op_sel_hi:[1,0]
	s_and_b64 vcc, exec, s[0:1]
	s_mov_b32 s59, s18
	s_mov_b32 s28, s20
	s_mov_b64 s[36:37], s[26:27]
	s_mov_b64 s[30:31], s[24:25]
	s_mov_b64 s[34:35], s[22:23]
	s_waitcnt vmcnt(4)
	v_cvt_f32_ubyte1_e32 v149, v132
	v_cvt_f32_ubyte0_e32 v148, v132
	v_cvt_f32_ubyte3_e32 v151, v132
	v_cvt_f32_ubyte2_e32 v150, v132
	v_cvt_f32_ubyte1_e32 v153, v133
	v_cvt_f32_ubyte0_e32 v152, v133
	v_cvt_f32_ubyte3_e32 v155, v133
	v_cvt_f32_ubyte2_e32 v154, v133
	v_cvt_f32_ubyte1_e32 v133, v134
	v_cvt_f32_ubyte0_e32 v132, v134
	v_cvt_f32_ubyte3_e32 v157, v134
	v_cvt_f32_ubyte2_e32 v156, v134
	v_cvt_f32_ubyte1_e32 v159, v135
	v_cvt_f32_ubyte0_e32 v158, v135
	v_cvt_f32_ubyte3_e32 v161, v135
	v_cvt_f32_ubyte2_e32 v160, v135
	v_cvt_f32_ubyte1_e32 v135, v136
	v_cvt_f32_ubyte0_e32 v134, v136
	v_cvt_f32_ubyte3_e32 v163, v136
	v_cvt_f32_ubyte2_e32 v162, v136
	v_cvt_f32_ubyte1_e32 v165, v137
	v_cvt_f32_ubyte0_e32 v164, v137
	v_cvt_f32_ubyte3_e32 v167, v137
	v_cvt_f32_ubyte2_e32 v166, v137
	v_pk_mul_f32 v[128:129], v[128:129], v[148:149]
	v_pk_mul_f32 v[130:131], v[130:131], v[150:151]
	v_pk_mul_f32 v[124:125], v[124:125], v[152:153]
	v_pk_mul_f32 v[126:127], v[126:127], v[154:155]
	v_pk_mul_f32 v[120:121], v[120:121], v[132:133]
	v_pk_mul_f32 v[122:123], v[122:123], v[156:157]
	v_pk_mul_f32 v[116:117], v[116:117], v[158:159]
	v_pk_mul_f32 v[118:119], v[118:119], v[160:161]
	v_pk_mul_f32 v[132:133], v[112:113], v[134:135]
	v_pk_mul_f32 v[134:135], v[114:115], v[162:163]
	v_pk_mul_f32 v[148:149], v[108:109], v[164:165]
	v_pk_mul_f32 v[150:151], v[110:111], v[166:167]
	v_cvt_pk_bf16_f32 v108, v128, v129
	v_cvt_pk_bf16_f32 v109, v130, v131
	v_cvt_pk_bf16_f32 v110, v124, v125
	v_cvt_pk_bf16_f32 v111, v126, v127
	v_cvt_pk_bf16_f32 v112, v120, v121
	v_cvt_pk_bf16_f32 v113, v122, v123
	v_cvt_pk_bf16_f32 v114, v116, v117
	v_cvt_pk_bf16_f32 v115, v118, v119
	v_cvt_pk_bf16_f32 v116, v132, v133
	v_cvt_pk_bf16_f32 v117, v134, v135
	v_cvt_pk_bf16_f32 v118, v148, v149
	v_cvt_pk_bf16_f32 v119, v150, v151
	buffer_store_dwordx4 v[108:111], v0, s[8:11], 0 offen
	buffer_store_dwordx4 v[112:115], v0, s[8:11], 0 offen offset:256
	buffer_store_dwordx4 v[116:119], v170, s[8:11], 0 offen
	v_cvt_f32_ubyte1_e32 v109, v139
	v_cvt_f32_ubyte0_e32 v108, v139
	v_pk_mul_f32 v[108:109], v[146:147], v[108:109]
	v_cvt_f32_ubyte1_e32 v137, v138
	v_cvt_pk_bf16_f32 v122, v108, v109
	v_cvt_f32_ubyte3_e32 v109, v139
	v_cvt_f32_ubyte2_e32 v108, v139
	v_pk_mul_f32 v[108:109], v[144:145], v[108:109]
	v_cvt_f32_ubyte0_e32 v136, v138
	v_cvt_pk_bf16_f32 v123, v108, v109
	v_pk_mul_f32 v[108:109], v[94:95], s[16:17] op_sel_hi:[1,0]
	v_pk_mul_f32 v[94:95], v[92:93], s[16:17] op_sel_hi:[1,0]
	v_cvt_f32_ubyte1_e32 v93, v104
	v_cvt_f32_ubyte0_e32 v92, v104
	v_pk_mul_f32 v[92:93], v[96:97], v[92:93]
	v_cvt_f32_ubyte3_e32 v97, v104
	v_cvt_f32_ubyte2_e32 v96, v104
	v_pk_mul_f32 v[96:97], v[98:99], v[96:97]
	v_cvt_pk_bf16_f32 v92, v92, v93
	v_cvt_pk_bf16_f32 v93, v96, v97
	v_cvt_f32_ubyte1_e32 v97, v105
	v_cvt_f32_ubyte0_e32 v96, v105
	v_cvt_f32_ubyte3_e32 v169, v138
	v_cvt_f32_ubyte2_e32 v168, v138
	v_pk_mul_f32 v[94:95], v[94:95], v[96:97]
	v_cvt_f32_ubyte3_e32 v97, v105
	v_cvt_f32_ubyte2_e32 v96, v105
	v_pk_mul_f32 v[136:137], v[142:143], v[136:137]
	v_pk_mul_f32 v[140:141], v[140:141], v[168:169]
	v_pk_mul_f32 v[96:97], v[108:109], v[96:97]
	v_cvt_pk_bf16_f32 v120, v136, v137
	v_cvt_pk_bf16_f32 v121, v140, v141
	v_add_u32_e32 v110, 0x10000, v0
	v_cvt_pk_bf16_f32 v94, v94, v95
	v_cvt_pk_bf16_f32 v95, v96, v97
	buffer_store_dwordx4 v[120:123], v170, s[8:11], 0 offen offset:256
	buffer_store_dwordx4 v[92:95], v110, s[8:11], 0 offen
	s_nop 1
	v_pk_mul_f32 v[92:93], v[86:87], s[16:17] op_sel_hi:[1,0]
	v_pk_mul_f32 v[86:87], v[84:85], s[16:17] op_sel_hi:[1,0]
	v_cvt_f32_ubyte1_e32 v85, v106
	v_cvt_f32_ubyte0_e32 v84, v106
	v_pk_mul_f32 v[84:85], v[88:89], v[84:85]
	v_cvt_f32_ubyte3_e32 v89, v106
	v_cvt_f32_ubyte2_e32 v88, v106
	v_pk_mul_f32 v[88:89], v[90:91], v[88:89]
	v_cvt_pk_bf16_f32 v84, v84, v85
	v_cvt_pk_bf16_f32 v85, v88, v89
	v_cvt_f32_ubyte1_e32 v89, v107
	v_cvt_f32_ubyte0_e32 v88, v107
	v_pk_mul_f32 v[86:87], v[86:87], v[88:89]
	v_cvt_f32_ubyte3_e32 v89, v107
	v_cvt_f32_ubyte2_e32 v88, v107
	v_pk_mul_f32 v[88:89], v[92:93], v[88:89]
	v_cvt_pk_bf16_f32 v86, v86, v87
	v_cvt_pk_bf16_f32 v87, v88, v89
	buffer_store_dwordx4 v[84:87], v110, s[8:11], 0 offen offset:256
	s_nop 1
	v_pk_mul_f32 v[84:85], v[78:79], s[16:17] op_sel_hi:[1,0]
	v_pk_mul_f32 v[78:79], v[76:77], s[16:17] op_sel_hi:[1,0]
	v_cvt_f32_ubyte1_e32 v77, v100
	v_cvt_f32_ubyte0_e32 v76, v100
	v_pk_mul_f32 v[76:77], v[80:81], v[76:77]
	v_cvt_f32_ubyte3_e32 v81, v100
	v_cvt_f32_ubyte2_e32 v80, v100
	v_pk_mul_f32 v[80:81], v[82:83], v[80:81]
	v_cvt_pk_bf16_f32 v76, v76, v77
	v_cvt_pk_bf16_f32 v77, v80, v81
	v_cvt_f32_ubyte1_e32 v81, v101
	v_cvt_f32_ubyte0_e32 v80, v101
	v_pk_mul_f32 v[78:79], v[78:79], v[80:81]
	v_cvt_f32_ubyte3_e32 v81, v101
	v_cvt_f32_ubyte2_e32 v80, v101
	v_pk_mul_f32 v[80:81], v[84:85], v[80:81]
	v_add_u32_e32 v86, 0x18000, v0
	v_cvt_pk_bf16_f32 v78, v78, v79
	v_cvt_pk_bf16_f32 v79, v80, v81
	buffer_store_dwordx4 v[76:79], v86, s[8:11], 0 offen
	v_add_u32_e32 v84, 0x40000, v0
	s_nop 0
	v_pk_mul_f32 v[76:77], v[70:71], s[16:17] op_sel_hi:[1,0]
	v_pk_mul_f32 v[70:71], v[68:69], s[16:17] op_sel_hi:[1,0]
	v_cvt_f32_ubyte1_e32 v69, v102
	v_cvt_f32_ubyte0_e32 v68, v102
	v_pk_mul_f32 v[68:69], v[72:73], v[68:69]
	v_cvt_f32_ubyte3_e32 v73, v102
	v_cvt_f32_ubyte2_e32 v72, v102
	v_pk_mul_f32 v[72:73], v[74:75], v[72:73]
	v_cvt_pk_bf16_f32 v68, v68, v69
	v_cvt_pk_bf16_f32 v69, v72, v73
	v_cvt_f32_ubyte1_e32 v73, v103
	v_cvt_f32_ubyte0_e32 v72, v103
	v_pk_mul_f32 v[70:71], v[70:71], v[72:73]
	v_cvt_f32_ubyte3_e32 v73, v103
	v_cvt_f32_ubyte2_e32 v72, v103
	v_pk_mul_f32 v[72:73], v[76:77], v[72:73]
	v_cvt_pk_bf16_f32 v70, v70, v71
	v_cvt_pk_bf16_f32 v71, v72, v73
	buffer_store_dwordx4 v[68:71], v86, s[8:11], 0 offen offset:256
	s_nop 0
	s_nop 0
	s_nop 0
	s_nop 0
	v_pk_mul_f32 v[2:3], v[66:67], s[16:17] op_sel_hi:[1,0]
	v_pk_mul_f32 v[66:67], v[62:63], s[16:17] op_sel_hi:[1,0]
	v_pk_mul_f32 v[62:63], v[60:61], s[16:17] op_sel_hi:[1,0]
	s_waitcnt vmcnt(8)
	v_cvt_f32_ubyte1_e32 v61, v224
	v_cvt_f32_ubyte0_e32 v60, v224
	v_pk_mul_f32 v[60:61], v[64:65], v[60:61]
	v_cvt_f32_ubyte3_e32 v65, v224
	v_cvt_f32_ubyte2_e32 v64, v224
	v_pk_mul_f32 v[2:3], v[2:3], v[64:65]
	v_cvt_pk_bf16_f32 v60, v60, v61
	v_cvt_pk_bf16_f32 v61, v2, v3
	v_cvt_f32_ubyte1_e32 v3, v225
	v_cvt_f32_ubyte0_e32 v2, v225
	v_pk_mul_f32 v[2:3], v[62:63], v[2:3]
	s_nop 0
	v_cvt_pk_bf16_f32 v62, v2, v3
	v_cvt_f32_ubyte3_e32 v3, v225
	v_cvt_f32_ubyte2_e32 v2, v225
	v_pk_mul_f32 v[2:3], v[66:67], v[2:3]
	s_nop 0
	v_cvt_pk_bf16_f32 v63, v2, v3
	v_pk_mul_f32 v[2:3], v[58:59], s[16:17] op_sel_hi:[1,0]
	v_pk_mul_f32 v[58:59], v[54:55], s[16:17] op_sel_hi:[1,0]
	v_pk_mul_f32 v[54:55], v[52:53], s[16:17] op_sel_hi:[1,0]
	v_cvt_f32_ubyte1_e32 v53, v226
	v_cvt_f32_ubyte0_e32 v52, v226
	v_pk_mul_f32 v[52:53], v[56:57], v[52:53]
	v_cvt_f32_ubyte3_e32 v57, v226
	v_cvt_f32_ubyte2_e32 v56, v226
	v_pk_mul_f32 v[2:3], v[2:3], v[56:57]
	v_cvt_pk_bf16_f32 v52, v52, v53
	v_cvt_pk_bf16_f32 v53, v2, v3
	v_cvt_f32_ubyte1_e32 v3, v227
	v_cvt_f32_ubyte0_e32 v2, v227
	v_pk_mul_f32 v[2:3], v[54:55], v[2:3]
	buffer_store_dwordx4 v[60:63], v84, s[8:11], 0 offen
	v_cvt_pk_bf16_f32 v54, v2, v3
	v_cvt_f32_ubyte3_e32 v3, v227
	v_cvt_f32_ubyte2_e32 v2, v227
	v_pk_mul_f32 v[2:3], v[58:59], v[2:3]
	s_nop 0
	v_cvt_pk_bf16_f32 v55, v2, v3
	v_pk_mul_f32 v[2:3], v[50:51], s[16:17] op_sel_hi:[1,0]
	v_pk_mul_f32 v[50:51], v[46:47], s[16:17] op_sel_hi:[1,0]
	v_pk_mul_f32 v[46:47], v[44:45], s[16:17] op_sel_hi:[1,0]
	s_nop 0
	v_cvt_f32_ubyte1_e32 v45, v228
	v_cvt_f32_ubyte0_e32 v44, v228
	v_pk_mul_f32 v[44:45], v[48:49], v[44:45]
	v_cvt_f32_ubyte3_e32 v49, v228
	v_cvt_f32_ubyte2_e32 v48, v228
	v_pk_mul_f32 v[2:3], v[2:3], v[48:49]
	v_cvt_pk_bf16_f32 v44, v44, v45
	v_cvt_pk_bf16_f32 v45, v2, v3
	v_cvt_f32_ubyte1_e32 v3, v229
	v_cvt_f32_ubyte0_e32 v2, v229
	v_pk_mul_f32 v[2:3], v[46:47], v[2:3]
	buffer_store_dwordx4 v[52:55], v84, s[8:11], 0 offen offset:256
	v_cvt_pk_bf16_f32 v46, v2, v3
	v_cvt_f32_ubyte3_e32 v3, v229
	v_cvt_f32_ubyte2_e32 v2, v229
	v_pk_mul_f32 v[2:3], v[50:51], v[2:3]
	v_add_u32_e32 v52, 0x48000, v0
	v_cvt_pk_bf16_f32 v47, v2, v3
	v_pk_mul_f32 v[2:3], v[42:43], s[16:17] op_sel_hi:[1,0]
	v_pk_mul_f32 v[42:43], v[38:39], s[16:17] op_sel_hi:[1,0]
	v_pk_mul_f32 v[38:39], v[36:37], s[16:17] op_sel_hi:[1,0]
	v_cvt_f32_ubyte1_e32 v37, v230
	v_cvt_f32_ubyte0_e32 v36, v230
	v_pk_mul_f32 v[36:37], v[40:41], v[36:37]
	v_cvt_f32_ubyte3_e32 v41, v230
	v_cvt_f32_ubyte2_e32 v40, v230
	v_pk_mul_f32 v[2:3], v[2:3], v[40:41]
	v_cvt_pk_bf16_f32 v36, v36, v37
	v_cvt_pk_bf16_f32 v37, v2, v3
	v_cvt_f32_ubyte1_e32 v3, v231
	v_cvt_f32_ubyte0_e32 v2, v231
	v_pk_mul_f32 v[2:3], v[38:39], v[2:3]
	buffer_store_dwordx4 v[44:47], v52, s[8:11], 0 offen
	v_cvt_pk_bf16_f32 v38, v2, v3
	v_cvt_f32_ubyte3_e32 v3, v231
	v_cvt_f32_ubyte2_e32 v2, v231
	v_pk_mul_f32 v[2:3], v[42:43], v[2:3]
	s_nop 0
	v_cvt_pk_bf16_f32 v39, v2, v3
	v_pk_mul_f32 v[2:3], v[34:35], s[16:17] op_sel_hi:[1,0]
	v_pk_mul_f32 v[34:35], v[30:31], s[16:17] op_sel_hi:[1,0]
	v_pk_mul_f32 v[30:31], v[28:29], s[16:17] op_sel_hi:[1,0]
	s_nop 0
	v_cvt_f32_ubyte1_e32 v29, v232
	v_cvt_f32_ubyte0_e32 v28, v232
	v_pk_mul_f32 v[28:29], v[32:33], v[28:29]
	v_cvt_f32_ubyte3_e32 v33, v232
	v_cvt_f32_ubyte2_e32 v32, v232
	v_pk_mul_f32 v[2:3], v[2:3], v[32:33]
	v_cvt_pk_bf16_f32 v28, v28, v29
	v_cvt_pk_bf16_f32 v29, v2, v3
	v_cvt_f32_ubyte1_e32 v3, v233
	v_cvt_f32_ubyte0_e32 v2, v233
	v_pk_mul_f32 v[2:3], v[30:31], v[2:3]
	buffer_store_dwordx4 v[36:39], v52, s[8:11], 0 offen offset:256
	v_cvt_pk_bf16_f32 v30, v2, v3
	v_cvt_f32_ubyte3_e32 v3, v233
	v_cvt_f32_ubyte2_e32 v2, v233
	v_pk_mul_f32 v[2:3], v[34:35], v[2:3]
	v_add_u32_e32 v36, 0x50000, v0
	v_cvt_pk_bf16_f32 v31, v2, v3
	v_pk_mul_f32 v[2:3], v[26:27], s[16:17] op_sel_hi:[1,0]
	v_pk_mul_f32 v[26:27], v[22:23], s[16:17] op_sel_hi:[1,0]
	v_pk_mul_f32 v[22:23], v[20:21], s[16:17] op_sel_hi:[1,0]
	v_cvt_f32_ubyte1_e32 v21, v234
	v_cvt_f32_ubyte0_e32 v20, v234
	v_pk_mul_f32 v[20:21], v[24:25], v[20:21]
	v_cvt_f32_ubyte3_e32 v25, v234
	v_cvt_f32_ubyte2_e32 v24, v234
	v_pk_mul_f32 v[2:3], v[2:3], v[24:25]
	v_cvt_pk_bf16_f32 v20, v20, v21
	v_cvt_pk_bf16_f32 v21, v2, v3
	v_cvt_f32_ubyte1_e32 v3, v235
	v_cvt_f32_ubyte0_e32 v2, v235
	v_pk_mul_f32 v[2:3], v[22:23], v[2:3]
	v_add_u32_e32 v0, 0x58000, v0
	v_cvt_pk_bf16_f32 v22, v2, v3
	v_cvt_f32_ubyte3_e32 v3, v235
	v_cvt_f32_ubyte2_e32 v2, v235
	v_pk_mul_f32 v[2:3], v[26:27], v[2:3]
	buffer_store_dwordx4 v[28:31], v36, s[8:11], 0 offen
	v_cvt_pk_bf16_f32 v23, v2, v3
	v_pk_mul_f32 v[2:3], v[18:19], s[16:17] op_sel_hi:[1,0]
	v_pk_mul_f32 v[18:19], v[14:15], s[16:17] op_sel_hi:[1,0]
	v_pk_mul_f32 v[14:15], v[12:13], s[16:17] op_sel_hi:[1,0]
	s_nop 0
	v_cvt_f32_ubyte1_e32 v13, v236
	v_cvt_f32_ubyte0_e32 v12, v236
	v_pk_mul_f32 v[12:13], v[16:17], v[12:13]
	v_cvt_f32_ubyte3_e32 v17, v236
	v_cvt_f32_ubyte2_e32 v16, v236
	v_pk_mul_f32 v[2:3], v[2:3], v[16:17]
	v_cvt_pk_bf16_f32 v12, v12, v13
	v_cvt_pk_bf16_f32 v13, v2, v3
	v_cvt_f32_ubyte1_e32 v3, v237
	v_cvt_f32_ubyte0_e32 v2, v237
	v_pk_mul_f32 v[2:3], v[14:15], v[2:3]
	buffer_store_dwordx4 v[20:23], v36, s[8:11], 0 offen offset:256
	v_cvt_pk_bf16_f32 v14, v2, v3
	v_cvt_f32_ubyte3_e32 v3, v237
	v_cvt_f32_ubyte2_e32 v2, v237
	v_pk_mul_f32 v[2:3], v[18:19], v[2:3]
	s_nop 0
	v_cvt_pk_bf16_f32 v15, v2, v3
	v_pk_mul_f32 v[2:3], v[8:9], s[16:17] op_sel_hi:[1,0]
	v_cvt_f32_ubyte1_e32 v9, v238
	v_cvt_f32_ubyte0_e32 v8, v238
	v_pk_mul_f32 v[2:3], v[2:3], v[8:9]
	v_cvt_f32_ubyte3_e32 v9, v238
	v_cvt_f32_ubyte2_e32 v8, v238
	v_pk_mul_f32 v[8:9], v[10:11], v[8:9]
	v_cvt_pk_bf16_f32 v2, v2, v3
	v_cvt_pk_bf16_f32 v3, v8, v9
	v_cvt_f32_ubyte1_e32 v9, v239
	v_cvt_f32_ubyte0_e32 v8, v239
	v_pk_mul_f32 v[4:5], v[4:5], v[8:9]
	v_cvt_f32_ubyte3_e32 v9, v239
	v_cvt_f32_ubyte2_e32 v8, v239
	v_pk_mul_f32 v[6:7], v[6:7], v[8:9]
	v_cvt_pk_bf16_f32 v4, v4, v5
	v_cvt_pk_bf16_f32 v5, v6, v7
	buffer_store_dwordx4 v[12:15], v0, s[8:11], 0 offen
	buffer_store_dwordx4 v[2:5], v0, s[8:11], 0 offen offset:256
	s_cbranch_vccnz .LBB0_431

.LBB0_434:
	s_cmp_gt_i32 s83, 4
	s_cselect_b64 s[0:1], -1, 0
	s_and_b64 s[4:5], s[6:7], s[0:1]
	s_andn2_b64 vcc, exec, s[4:5]
	s_cbranch_vccnz .LBB0_488
	s_waitcnt vmcnt(0)
	s_waitcnt vmcnt(0)
	s_barrier
	s_and_saveexec_b64 s[4:5], s[94:95]
	s_cbranch_execz .LBB0_487
	s_cmp_eq_u32 s32, 0
	s_cbranch_scc1 .Lxb_loc_3
	buffer_wbl2 sc1
	s_waitcnt vmcnt(0)
.Lxb_loc_3:
	v_mov_b32_e32 v1, 0x23ff0
	ds_read_b32 v2, v1
	ds_read_b32 v3, v1 offset:4
	s_add_u32 s6, s80, 0x2380000
	s_addc_u32 s7, s81, 0
	s_lshl_b32 s8, s87, 8
	s_add_i32 s9, s8, 0x1400
	s_add_i32 s8, s8, 0x2400
	v_mov_b32_e32 v4, s9
	v_mov_b32_e32 v5, 1
	global_atomic_add v6, v4, v5, s[6:7] sc0
	buffer_inv sc1
	s_waitcnt vmcnt(0) lgkmcnt(0)
	v_readfirstlane_b32 s10, v6
	v_readfirstlane_b32 s11, v2
	v_readfirstlane_b32 s16, v3
	s_add_i32 s10, s10, 1
	s_mul_i32 s11, s11, 4
	s_cmp_lg_u32 s10, s11
	s_cbranch_scc1 .Lxb_nl_3
	v_mov_b32_e32 v4, 0x3400
	global_atomic_add v6, v4, v5, s[6:7] sc0
	s_waitcnt vmcnt(0)
	v_readfirstlane_b32 s10, v6
	s_add_i32 s10, s10, 1
	s_mul_i32 s16, s16, 4
	s_cmp_lg_u32 s10, s16
	s_cbranch_scc1 .Lxb_nl_3
	v_mov_b32_e32 v4, 0x2400
	global_atomic_add v4, v5, s[6:7]
	global_atomic_add v4, v5, s[6:7] offset:256
	global_atomic_add v4, v5, s[6:7] offset:512
	global_atomic_add v4, v5, s[6:7] offset:768
	global_atomic_add v4, v5, s[6:7] offset:1024
	global_atomic_add v4, v5, s[6:7] offset:1280
	global_atomic_add v4, v5, s[6:7] offset:1536
	global_atomic_add v4, v5, s[6:7] offset:1792
	global_atomic_add v4, v5, s[6:7] offset:2048
	global_atomic_add v4, v5, s[6:7] offset:2304
	global_atomic_add v4, v5, s[6:7] offset:2560
	global_atomic_add v4, v5, s[6:7] offset:2816
	global_atomic_add v4, v5, s[6:7] offset:3072
	global_atomic_add v4, v5, s[6:7] offset:3328
	global_atomic_add v4, v5, s[6:7] offset:3584
	global_atomic_add v4, v5, s[6:7] offset:3840
	s_branch .Lxb_done_3

.LBB0_507:
	s_lshl_b32 s19, s38, 8
	v_lshl_or_b32 v222, s18, 8, v199
	v_add_u32_e32 v192, s19, v197
	v_ashrrev_i32_e32 v223, 31, v222
	v_ashrrev_i32_e32 v193, 31, v192
	v_lshl_add_u64 v[194:195], v[222:223], 2, s[40:41]
	v_lshlrev_b64 v[128:129], 12, v[192:193]
	v_lshl_add_u64 v[128:129], v[194:195], 0, v[128:129]
	global_load_dwordx4 v[224:227], v[128:129], off nt
	global_load_dwordx4 v[228:231], v[128:129], off offset:16 nt
	global_load_dwordx4 v[232:235], v[128:129], off offset:512 nt
	global_load_dwordx4 v[236:239], v[128:129], off offset:528 nt
	v_or_b32_e32 v128, 16, v192
	v_or_b32_e32 v130, 32, v192
	v_or_b32_e32 v132, 48, v192
	v_ashrrev_i32_e32 v129, 31, v128
	v_ashrrev_i32_e32 v131, 31, v130
	v_ashrrev_i32_e32 v133, 31, v132
	v_lshlrev_b64 v[128:129], 12, v[128:129]
	v_lshlrev_b64 v[130:131], 12, v[130:131]
	v_lshlrev_b64 v[132:133], 12, v[132:133]
	v_lshl_add_u64 v[128:129], v[194:195], 0, v[128:129]
	v_lshl_add_u64 v[130:131], v[194:195], 0, v[130:131]
	v_lshl_add_u64 v[132:133], v[194:195], 0, v[132:133]
	global_load_dwordx4 v[168:171], v[128:129], off offset:16 nt
	global_load_dwordx4 v[172:175], v[128:129], off nt
	global_load_dwordx4 v[160:163], v[128:129], off offset:528 nt
	global_load_dwordx4 v[164:167], v[128:129], off offset:512 nt
	global_load_dwordx4 v[152:155], v[130:131], off offset:16 nt
	global_load_dwordx4 v[156:159], v[130:131], off nt
	global_load_dwordx4 v[144:147], v[130:131], off offset:528 nt
	global_load_dwordx4 v[148:151], v[130:131], off offset:512 nt
	global_load_dwordx4 v[136:139], v[132:133], off offset:16 nt
	global_load_dwordx4 v[140:143], v[132:133], off nt
	s_nop 0
	global_load_dwordx4 v[128:131], v[132:133], off offset:528 nt
	s_nop 0
	global_load_dwordx4 v[132:135], v[132:133], off offset:512 nt
	v_and_b32_e32 v221, 64, v220
	v_xor_b32_e32 v193, 16, v220
	v_add_u32_e32 v221, 64, v221
	v_xor_b32_e32 v223, 32, v220
	v_cmp_lt_i32_e32 vcc, v193, v221
	s_lshl_b32 s20, s38, 19
	v_lshl_add_u32 v222, v222, 1, s20
	v_cndmask_b32_e32 v193, v220, v193, vcc
	v_cmp_lt_i32_e32 vcc, v223, v221
	v_lshlrev_b32_e32 v221, 2, v193
	v_add_u32_e32 v240, v222, v200
	v_cndmask_b32_e32 v223, v220, v223, vcc
	v_lshlrev_b32_e32 v193, 2, v223
	s_waitcnt vmcnt(0)
	v_pk_add_f32 v[126:127], v[126:127], v[226:227]
	v_pk_add_f32 v[124:125], v[124:125], v[224:225]
	v_pk_add_f32 v[122:123], v[122:123], v[230:231]
	v_pk_add_f32 v[120:121], v[120:121], v[228:229]
	v_pk_add_f32 v[118:119], v[118:119], v[234:235]
	v_pk_add_f32 v[116:117], v[116:117], v[232:233]
	v_pk_add_f32 v[224:225], v[114:115], v[238:239]
	v_pk_add_f32 v[226:227], v[112:113], v[236:237]
	v_cvt_pk_bf16_f32 v112, v124, v125
	v_cvt_pk_bf16_f32 v113, v126, v127
	v_mul_f32_e32 v114, v125, v125
	v_mul_f32_e32 v115, v127, v127
	v_mul_f32_e32 v125, v121, v121
	v_mul_f32_e32 v127, v123, v123
	v_mul_f32_e32 v223, v117, v117
	v_mul_f32_e32 v228, v119, v119
	v_mul_f32_e32 v229, v227, v227
	v_mul_f32_e32 v230, v225, v225
	v_fmac_f32_e32 v114, v124, v124
	v_fmac_f32_e32 v115, v126, v126
	v_fmac_f32_e32 v125, v120, v120
	v_fmac_f32_e32 v127, v122, v122
	v_fmac_f32_e32 v223, v116, v116
	v_fmac_f32_e32 v228, v118, v118
	v_fmac_f32_e32 v229, v226, v226
	v_fmac_f32_e32 v230, v224, v224
	v_add_f32_e32 v114, v114, v115
	v_add_f32_e32 v115, v125, v127
	v_add_f32_e32 v124, v223, v228
	v_add_f32_e32 v125, v229, v230
	v_add_f32_e32 v114, v114, v115
	v_add_f32_e32 v115, v124, v125
	v_add_f32_e32 v124, v114, v115
	ds_bpermute_b32 v125, v221, v124
	v_cvt_pk_bf16_f32 v114, v120, v121
	v_cvt_pk_bf16_f32 v115, v122, v123
	buffer_store_dwordx4 v[112:115], v240, s[8:11], 0 offen
	s_waitcnt lgkmcnt(0)
	s_nop 0
	v_add_f32_e32 v112, v124, v125
	ds_bpermute_b32 v113, v193, v112
	v_cvt_pk_bf16_f32 v114, v116, v117
	v_cvt_pk_bf16_f32 v115, v118, v119
	v_cvt_pk_bf16_f32 v116, v226, v227
	v_cvt_pk_bf16_f32 v117, v224, v225
	buffer_store_dwordx4 v[114:117], v240, s[8:11], 0 offen offset:256
	s_and_saveexec_b64 s[38:39], s[0:1]
	s_cbranch_execz .LBB0_509
	s_waitcnt lgkmcnt(0)
	v_add_f32_e32 v112, v112, v113
	ds_write_b32 v208, v112
.LBB0_509:
	s_or_b64 exec, exec, s[38:39]
	v_pk_add_f32 v[108:109], v[108:109], v[172:173]
	v_pk_add_f32 v[110:111], v[110:111], v[174:175]
	s_waitcnt lgkmcnt(0)
	v_pk_add_f32 v[112:113], v[106:107], v[170:171]
	v_pk_add_f32 v[106:107], v[104:105], v[168:169]
	v_cvt_pk_bf16_f32 v104, v108, v109
	v_mul_f32_e32 v109, v109, v109
	v_fmac_f32_e32 v109, v108, v108
	v_mul_f32_e32 v108, v111, v111
	v_fmac_f32_e32 v108, v110, v110
	v_cvt_pk_bf16_f32 v105, v110, v111
	v_add_f32_e32 v108, v109, v108
	v_mul_f32_e32 v109, v107, v107
	v_mul_f32_e32 v110, v113, v113
	v_fmac_f32_e32 v109, v106, v106
	v_fmac_f32_e32 v110, v112, v112
	v_pk_add_f32 v[102:103], v[102:103], v[166:167]
	v_pk_add_f32 v[100:101], v[100:101], v[164:165]
	v_add_f32_e32 v109, v109, v110
	v_pk_add_f32 v[110:111], v[96:97], v[160:161]
	v_mul_f32_e32 v96, v101, v101
	v_mul_f32_e32 v97, v103, v103
	v_add_f32_e32 v115, v108, v109
	v_pk_add_f32 v[108:109], v[98:99], v[162:163]
	v_fmac_f32_e32 v96, v100, v100
	v_fmac_f32_e32 v97, v102, v102
	v_add_f32_e32 v96, v96, v97
	v_mul_f32_e32 v97, v111, v111
	v_mul_f32_e32 v98, v109, v109
	v_fmac_f32_e32 v97, v110, v110
	v_fmac_f32_e32 v98, v108, v108
	v_add_f32_e32 v97, v97, v98
	v_add_f32_e32 v96, v96, v97
	v_add_f32_e32 v96, v115, v96
	ds_bpermute_b32 v97, v221, v96
	v_add_u32_e32 v114, v222, v201
	v_cvt_pk_bf16_f32 v106, v106, v107
	v_cvt_pk_bf16_f32 v107, v112, v113
	v_cvt_pk_bf16_f32 v98, v100, v101
	s_waitcnt lgkmcnt(0)
	v_add_f32_e32 v96, v96, v97
	ds_bpermute_b32 v97, v193, v96
	v_cvt_pk_bf16_f32 v99, v102, v103
	v_cvt_pk_bf16_f32 v100, v110, v111
	v_cvt_pk_bf16_f32 v101, v108, v109
	buffer_store_dwordx4 v[104:107], v114, s[8:11], 0 offen
	buffer_store_dwordx4 v[98:101], v114, s[8:11], 0 offen offset:256
	s_and_saveexec_b64 s[38:39], s[0:1]
	s_cbranch_execz .LBB0_511
	s_waitcnt lgkmcnt(0)
	v_add_f32_e32 v96, v96, v97
	ds_write_b32 v209, v96
.LBB0_511:
	s_or_b64 exec, exec, s[38:39]
	v_pk_add_f32 v[92:93], v[92:93], v[156:157]
	v_pk_add_f32 v[94:95], v[94:95], v[158:159]
	s_waitcnt lgkmcnt(0)
	v_pk_add_f32 v[96:97], v[90:91], v[154:155]
	v_pk_add_f32 v[90:91], v[88:89], v[152:153]
	v_cvt_pk_bf16_f32 v88, v92, v93
	v_mul_f32_e32 v93, v93, v93
	v_fmac_f32_e32 v93, v92, v92
	v_mul_f32_e32 v92, v95, v95
	v_fmac_f32_e32 v92, v94, v94
	v_cvt_pk_bf16_f32 v89, v94, v95
	v_add_f32_e32 v92, v93, v92
	v_mul_f32_e32 v93, v91, v91
	v_mul_f32_e32 v94, v97, v97
	v_fmac_f32_e32 v93, v90, v90
	v_fmac_f32_e32 v94, v96, v96
	v_pk_add_f32 v[86:87], v[86:87], v[150:151]
	v_pk_add_f32 v[84:85], v[84:85], v[148:149]
	v_add_f32_e32 v93, v93, v94
	v_pk_add_f32 v[94:95], v[80:81], v[144:145]
	v_mul_f32_e32 v80, v85, v85
	v_mul_f32_e32 v81, v87, v87
	v_add_f32_e32 v99, v92, v93
	v_pk_add_f32 v[92:93], v[82:83], v[146:147]
	v_fmac_f32_e32 v80, v84, v84
	v_fmac_f32_e32 v81, v86, v86
	v_add_f32_e32 v80, v80, v81
	v_mul_f32_e32 v81, v95, v95
	v_mul_f32_e32 v82, v93, v93
	v_fmac_f32_e32 v81, v94, v94
	v_fmac_f32_e32 v82, v92, v92
	v_add_f32_e32 v81, v81, v82
	v_add_f32_e32 v80, v80, v81
	v_add_f32_e32 v80, v99, v80
	ds_bpermute_b32 v81, v221, v80
	v_add_u32_e32 v98, v222, v202
	v_cvt_pk_bf16_f32 v90, v90, v91
	v_cvt_pk_bf16_f32 v91, v96, v97
	v_cvt_pk_bf16_f32 v82, v84, v85
	s_waitcnt lgkmcnt(0)
	v_add_f32_e32 v80, v80, v81
	ds_bpermute_b32 v81, v193, v80
	v_cvt_pk_bf16_f32 v83, v86, v87
	v_cvt_pk_bf16_f32 v84, v94, v95
	v_cvt_pk_bf16_f32 v85, v92, v93
	buffer_store_dwordx4 v[88:91], v98, s[8:11], 0 offen
	buffer_store_dwordx4 v[82:85], v98, s[8:11], 0 offen offset:256
	s_and_saveexec_b64 s[38:39], s[0:1]
	s_cbranch_execz .LBB0_513
	s_waitcnt lgkmcnt(0)
	v_add_f32_e32 v80, v80, v81
	ds_write_b32 v210, v80
.LBB0_513:
	s_or_b64 exec, exec, s[38:39]
	v_pk_add_f32 v[76:77], v[76:77], v[140:141]
	v_pk_add_f32 v[78:79], v[78:79], v[142:143]
	s_waitcnt lgkmcnt(0)
	v_pk_add_f32 v[80:81], v[74:75], v[138:139]
	v_pk_add_f32 v[74:75], v[72:73], v[136:137]
	v_cvt_pk_bf16_f32 v72, v76, v77
	v_mul_f32_e32 v77, v77, v77
	v_fmac_f32_e32 v77, v76, v76
	v_mul_f32_e32 v76, v79, v79
	v_fmac_f32_e32 v76, v78, v78
	v_cvt_pk_bf16_f32 v73, v78, v79
	v_add_f32_e32 v76, v77, v76
	v_mul_f32_e32 v77, v75, v75
	v_mul_f32_e32 v78, v81, v81
	v_fmac_f32_e32 v77, v74, v74
	v_fmac_f32_e32 v78, v80, v80
	v_pk_add_f32 v[70:71], v[70:71], v[134:135]
	v_pk_add_f32 v[68:69], v[68:69], v[132:133]
	v_add_f32_e32 v77, v77, v78
	v_pk_add_f32 v[78:79], v[64:65], v[128:129]
	v_mul_f32_e32 v64, v69, v69
	v_mul_f32_e32 v65, v71, v71
	v_add_f32_e32 v83, v76, v77
	v_pk_add_f32 v[76:77], v[66:67], v[130:131]
	v_fmac_f32_e32 v64, v68, v68
	v_fmac_f32_e32 v65, v70, v70
	v_add_f32_e32 v64, v64, v65
	v_mul_f32_e32 v65, v79, v79
	v_mul_f32_e32 v66, v77, v77
	v_fmac_f32_e32 v65, v78, v78
	v_fmac_f32_e32 v66, v76, v76
	v_add_f32_e32 v65, v65, v66
	v_add_f32_e32 v64, v64, v65
	v_add_f32_e32 v64, v83, v64
	ds_bpermute_b32 v65, v221, v64
	v_add_u32_e32 v82, v222, v203
	v_cvt_pk_bf16_f32 v74, v74, v75
	v_cvt_pk_bf16_f32 v75, v80, v81
	v_cvt_pk_bf16_f32 v66, v68, v69
	s_waitcnt lgkmcnt(0)
	v_add_f32_e32 v64, v64, v65
	ds_bpermute_b32 v65, v193, v64
	v_cvt_pk_bf16_f32 v67, v70, v71
	v_cvt_pk_bf16_f32 v68, v78, v79
	v_cvt_pk_bf16_f32 v69, v76, v77
	buffer_store_dwordx4 v[72:75], v82, s[8:11], 0 offen
	buffer_store_dwordx4 v[66:69], v82, s[8:11], 0 offen offset:256
	s_and_saveexec_b64 s[38:39], s[0:1]
	s_cbranch_execz .LBB0_515
	s_waitcnt lgkmcnt(0)
	v_add_f32_e32 v64, v64, v65
	ds_write_b32 v211, v64
.LBB0_515:
	s_or_b64 exec, exec, s[38:39]
	v_add_u32_e32 v64, 0x80, v192
	s_waitcnt lgkmcnt(0)
	v_ashrrev_i32_e32 v65, 31, v64
	v_lshlrev_b64 v[64:65], 12, v[64:65]
	v_lshl_add_u64 v[64:65], v[194:195], 0, v[64:65]
	global_load_dwordx4 v[112:115], v[64:65], off nt
	global_load_dwordx4 v[116:119], v[64:65], off offset:16 nt
	global_load_dwordx4 v[120:123], v[64:65], off offset:512 nt
	global_load_dwordx4 v[124:127], v[64:65], off offset:528 nt
	v_add_u32_e32 v64, 0x90, v192
	v_add_u32_e32 v66, 0xa0, v192
	v_add_u32_e32 v68, 0xb0, v192
	v_ashrrev_i32_e32 v65, 31, v64
	v_ashrrev_i32_e32 v67, 31, v66
	v_ashrrev_i32_e32 v69, 31, v68
	v_lshlrev_b64 v[64:65], 12, v[64:65]
	v_lshlrev_b64 v[66:67], 12, v[66:67]
	v_lshlrev_b64 v[68:69], 12, v[68:69]
	v_lshl_add_u64 v[64:65], v[194:195], 0, v[64:65]
	v_lshl_add_u64 v[66:67], v[194:195], 0, v[66:67]
	v_lshl_add_u64 v[68:69], v[194:195], 0, v[68:69]
	global_load_dwordx4 v[104:107], v[64:65], off offset:16 nt
	global_load_dwordx4 v[108:111], v[64:65], off nt
	global_load_dwordx4 v[96:99], v[64:65], off offset:528 nt
	global_load_dwordx4 v[100:103], v[64:65], off offset:512 nt
	global_load_dwordx4 v[88:91], v[66:67], off offset:16 nt
	global_load_dwordx4 v[92:95], v[66:67], off nt
	global_load_dwordx4 v[80:83], v[66:67], off offset:528 nt
	global_load_dwordx4 v[84:87], v[66:67], off offset:512 nt
	global_load_dwordx4 v[72:75], v[68:69], off offset:16 nt
	global_load_dwordx4 v[76:79], v[68:69], off nt
	s_nop 0
	global_load_dwordx4 v[64:67], v[68:69], off offset:528 nt
	s_nop 0
	global_load_dwordx4 v[68:71], v[68:69], off offset:512 nt
	v_add_u32_e32 v128, v222, v204
	s_waitcnt vmcnt(15)
	v_pk_add_f32 v[62:63], v[62:63], v[114:115]
	v_pk_add_f32 v[60:61], v[60:61], v[112:113]
	s_waitcnt vmcnt(14)
	v_pk_add_f32 v[58:59], v[58:59], v[118:119]
	v_pk_add_f32 v[56:57], v[56:57], v[116:117]
	s_waitcnt vmcnt(13)
	v_pk_add_f32 v[54:55], v[54:55], v[122:123]
	v_pk_add_f32 v[52:53], v[52:53], v[120:121]
	s_waitcnt vmcnt(12)
	v_pk_add_f32 v[112:113], v[50:51], v[126:127]
	v_pk_add_f32 v[114:115], v[48:49], v[124:125]
	v_cvt_pk_bf16_f32 v48, v60, v61
	v_cvt_pk_bf16_f32 v49, v62, v63
	v_mul_f32_e32 v50, v61, v61
	v_mul_f32_e32 v51, v63, v63
	v_mul_f32_e32 v61, v57, v57
	v_mul_f32_e32 v63, v59, v59
	v_mul_f32_e32 v116, v53, v53
	v_mul_f32_e32 v117, v55, v55
	v_mul_f32_e32 v118, v115, v115
	v_mul_f32_e32 v119, v113, v113
	v_fmac_f32_e32 v50, v60, v60
	v_fmac_f32_e32 v51, v62, v62
	v_fmac_f32_e32 v61, v56, v56
	v_fmac_f32_e32 v63, v58, v58
	v_fmac_f32_e32 v116, v52, v52
	v_fmac_f32_e32 v117, v54, v54
	v_fmac_f32_e32 v118, v114, v114
	v_fmac_f32_e32 v119, v112, v112
	v_add_f32_e32 v50, v50, v51
	v_add_f32_e32 v51, v61, v63
	v_add_f32_e32 v60, v116, v117
	v_add_f32_e32 v61, v118, v119
	v_add_f32_e32 v50, v50, v51
	v_add_f32_e32 v51, v60, v61
	v_add_f32_e32 v60, v50, v51
	ds_bpermute_b32 v61, v221, v60
	v_cvt_pk_bf16_f32 v50, v56, v57
	v_cvt_pk_bf16_f32 v51, v58, v59
	buffer_store_dwordx4 v[48:51], v128, s[8:11], 0 offen
	s_waitcnt lgkmcnt(0)
	s_nop 0
	v_add_f32_e32 v48, v60, v61
	ds_bpermute_b32 v49, v193, v48
	v_cvt_pk_bf16_f32 v50, v52, v53
	v_cvt_pk_bf16_f32 v51, v54, v55
	v_cvt_pk_bf16_f32 v52, v114, v115
	v_cvt_pk_bf16_f32 v53, v112, v113
	buffer_store_dwordx4 v[50:53], v128, s[8:11], 0 offen offset:256
	s_and_saveexec_b64 s[38:39], s[0:1]
	s_cbranch_execz .LBB0_517
	s_waitcnt lgkmcnt(0)
	v_add_f32_e32 v48, v48, v49
	ds_write_b32 v212, v48
.LBB0_517:
	s_or_b64 exec, exec, s[38:39]
	s_waitcnt vmcnt(12)
	v_pk_add_f32 v[44:45], v[44:45], v[108:109]
	v_pk_add_f32 v[46:47], v[46:47], v[110:111]
	s_waitcnt lgkmcnt(0)
	v_pk_add_f32 v[48:49], v[42:43], v[106:107]
	v_pk_add_f32 v[42:43], v[40:41], v[104:105]
	v_cvt_pk_bf16_f32 v40, v44, v45
	v_mul_f32_e32 v45, v45, v45
	v_fmac_f32_e32 v45, v44, v44
	v_mul_f32_e32 v44, v47, v47
	v_fmac_f32_e32 v44, v46, v46
	v_cvt_pk_bf16_f32 v41, v46, v47
	v_add_f32_e32 v44, v45, v44
	v_mul_f32_e32 v45, v43, v43
	v_mul_f32_e32 v46, v49, v49
	v_fmac_f32_e32 v45, v42, v42
	v_fmac_f32_e32 v46, v48, v48
	s_waitcnt vmcnt(10)
	v_pk_add_f32 v[38:39], v[38:39], v[102:103]
	v_pk_add_f32 v[36:37], v[36:37], v[100:101]
	v_add_f32_e32 v45, v45, v46
	v_pk_add_f32 v[46:47], v[32:33], v[96:97]
	v_mul_f32_e32 v32, v37, v37
	v_mul_f32_e32 v33, v39, v39
	v_add_f32_e32 v51, v44, v45
	v_pk_add_f32 v[44:45], v[34:35], v[98:99]
	v_fmac_f32_e32 v32, v36, v36
	v_fmac_f32_e32 v33, v38, v38
	v_add_f32_e32 v32, v32, v33
	v_mul_f32_e32 v33, v47, v47
	v_mul_f32_e32 v34, v45, v45
	v_fmac_f32_e32 v33, v46, v46
	v_fmac_f32_e32 v34, v44, v44
	v_add_f32_e32 v33, v33, v34
	v_add_f32_e32 v32, v32, v33
	v_add_f32_e32 v32, v51, v32
	ds_bpermute_b32 v33, v221, v32
	v_add_u32_e32 v50, v222, v205
	v_cvt_pk_bf16_f32 v42, v42, v43
	v_cvt_pk_bf16_f32 v43, v48, v49
	v_cvt_pk_bf16_f32 v34, v36, v37
	s_waitcnt lgkmcnt(0)
	v_add_f32_e32 v32, v32, v33
	ds_bpermute_b32 v33, v193, v32
	v_cvt_pk_bf16_f32 v35, v38, v39
	v_cvt_pk_bf16_f32 v36, v46, v47
	v_cvt_pk_bf16_f32 v37, v44, v45
	buffer_store_dwordx4 v[40:43], v50, s[8:11], 0 offen
	buffer_store_dwordx4 v[34:37], v50, s[8:11], 0 offen offset:256
	s_and_saveexec_b64 s[38:39], s[0:1]
	s_cbranch_execz .LBB0_519
	s_waitcnt lgkmcnt(0)
	v_add_f32_e32 v32, v32, v33
	ds_write_b32 v213, v32
.LBB0_519:
	s_or_b64 exec, exec, s[38:39]
	s_waitcnt vmcnt(10)
	v_pk_add_f32 v[28:29], v[28:29], v[92:93]
	v_pk_add_f32 v[30:31], v[30:31], v[94:95]
	s_waitcnt lgkmcnt(0)
	v_pk_add_f32 v[32:33], v[26:27], v[90:91]
	v_pk_add_f32 v[26:27], v[24:25], v[88:89]
	v_cvt_pk_bf16_f32 v24, v28, v29
	v_mul_f32_e32 v29, v29, v29
	v_fmac_f32_e32 v29, v28, v28
	v_mul_f32_e32 v28, v31, v31
	v_fmac_f32_e32 v28, v30, v30
	v_cvt_pk_bf16_f32 v25, v30, v31
	v_add_f32_e32 v28, v29, v28
	v_mul_f32_e32 v29, v27, v27
	v_mul_f32_e32 v30, v33, v33
	v_fmac_f32_e32 v29, v26, v26
	v_fmac_f32_e32 v30, v32, v32
	s_waitcnt vmcnt(8)
	v_pk_add_f32 v[22:23], v[22:23], v[86:87]
	v_pk_add_f32 v[20:21], v[20:21], v[84:85]
	v_add_f32_e32 v29, v29, v30
	v_pk_add_f32 v[30:31], v[16:17], v[80:81]
	v_mul_f32_e32 v16, v21, v21
	v_mul_f32_e32 v17, v23, v23
	v_add_f32_e32 v35, v28, v29
	v_pk_add_f32 v[28:29], v[18:19], v[82:83]
	v_fmac_f32_e32 v16, v20, v20
	v_fmac_f32_e32 v17, v22, v22
	v_add_f32_e32 v16, v16, v17
	v_mul_f32_e32 v17, v31, v31
	v_mul_f32_e32 v18, v29, v29
	v_fmac_f32_e32 v17, v30, v30
	v_fmac_f32_e32 v18, v28, v28
	v_add_f32_e32 v17, v17, v18
	v_add_f32_e32 v16, v16, v17
	v_add_f32_e32 v16, v35, v16
	ds_bpermute_b32 v17, v221, v16
	v_add_u32_e32 v34, v222, v206
	v_cvt_pk_bf16_f32 v26, v26, v27
	v_cvt_pk_bf16_f32 v27, v32, v33
	v_cvt_pk_bf16_f32 v18, v20, v21
	s_waitcnt lgkmcnt(0)
	v_add_f32_e32 v16, v16, v17
	ds_bpermute_b32 v17, v193, v16
	v_cvt_pk_bf16_f32 v19, v22, v23
	v_cvt_pk_bf16_f32 v20, v30, v31
	v_cvt_pk_bf16_f32 v21, v28, v29
	buffer_store_dwordx4 v[24:27], v34, s[8:11], 0 offen
	buffer_store_dwordx4 v[18:21], v34, s[8:11], 0 offen offset:256
	s_and_saveexec_b64 s[38:39], s[0:1]
	s_cbranch_execz .LBB0_521
	s_waitcnt lgkmcnt(0)
	v_add_f32_e32 v16, v16, v17
	ds_write_b32 v214, v16
.LBB0_521:
	s_or_b64 exec, exec, s[38:39]
	s_waitcnt vmcnt(8)
	v_pk_add_f32 v[12:13], v[12:13], v[76:77]
	v_pk_add_f32 v[14:15], v[14:15], v[78:79]
	s_waitcnt lgkmcnt(0)
	v_pk_add_f32 v[16:17], v[10:11], v[74:75]
	v_pk_add_f32 v[10:11], v[8:9], v[72:73]
	v_cvt_pk_bf16_f32 v8, v12, v13
	v_mul_f32_e32 v13, v13, v13
	v_fmac_f32_e32 v13, v12, v12
	v_mul_f32_e32 v12, v15, v15
	v_fmac_f32_e32 v12, v14, v14
	v_cvt_pk_bf16_f32 v9, v14, v15
	v_add_f32_e32 v12, v13, v12
	v_mul_f32_e32 v13, v11, v11
	v_mul_f32_e32 v14, v17, v17
	v_fmac_f32_e32 v13, v10, v10
	v_fmac_f32_e32 v14, v16, v16
	s_waitcnt vmcnt(6)
	v_pk_add_f32 v[6:7], v[6:7], v[70:71]
	v_pk_add_f32 v[4:5], v[4:5], v[68:69]
	v_add_f32_e32 v13, v13, v14
	v_pk_add_f32 v[14:15], v[0:1], v[64:65]
	v_mul_f32_e32 v0, v5, v5
	v_mul_f32_e32 v1, v7, v7
	v_add_f32_e32 v19, v12, v13
	v_pk_add_f32 v[12:13], v[2:3], v[66:67]
	v_fmac_f32_e32 v0, v4, v4
	v_fmac_f32_e32 v1, v6, v6
	v_add_f32_e32 v0, v0, v1
	v_mul_f32_e32 v1, v15, v15
	v_mul_f32_e32 v2, v13, v13
	v_fmac_f32_e32 v1, v14, v14
	v_fmac_f32_e32 v2, v12, v12
	v_add_f32_e32 v1, v1, v2
	v_add_f32_e32 v0, v0, v1
	v_add_f32_e32 v0, v19, v0
	ds_bpermute_b32 v1, v221, v0
	v_add_u32_e32 v18, v222, v207
	v_cvt_pk_bf16_f32 v10, v10, v11
	v_cvt_pk_bf16_f32 v11, v16, v17
	v_cvt_pk_bf16_f32 v2, v4, v5
	s_waitcnt lgkmcnt(0)
	v_add_f32_e32 v0, v0, v1
	ds_bpermute_b32 v1, v193, v0
	v_cvt_pk_bf16_f32 v3, v6, v7
	v_cvt_pk_bf16_f32 v4, v14, v15
	v_cvt_pk_bf16_f32 v5, v12, v13
	buffer_store_dwordx4 v[8:11], v18, s[8:11], 0 offen
	buffer_store_dwordx4 v[2:5], v18, s[8:11], 0 offen offset:256
	s_and_saveexec_b64 s[38:39], s[0:1]
	s_cbranch_execz .LBB0_523
	s_waitcnt lgkmcnt(0)
	v_add_f32_e32 v0, v0, v1
	ds_write_b32 v215, v0

.LBB0_529:
	s_cmp_gt_i32 s83, 5
	s_cselect_b64 s[0:1], -1, 0
	s_and_b64 s[4:5], s[16:17], s[0:1]
	s_andn2_b64 vcc, exec, s[4:5]
	s_cbranch_vccnz .LBB0_583
	s_waitcnt vmcnt(0)
	s_waitcnt vmcnt(0) lgkmcnt(0)
	s_barrier
	s_and_saveexec_b64 s[4:5], s[94:95]
	s_cbranch_execz .LBB0_582
	s_cmp_eq_u32 s32, 0
	s_cbranch_scc1 .Lxb_loc_4
	buffer_wbl2 sc1
	s_waitcnt vmcnt(0)
.Lxb_loc_4:
	v_mov_b32_e32 v1, 0x23ff0
	ds_read_b32 v2, v1
	ds_read_b32 v3, v1 offset:4
	s_add_u32 s6, s80, 0x2380000
	s_addc_u32 s7, s81, 0
	s_lshl_b32 s8, s87, 8
	s_add_i32 s9, s8, 0x1400
	s_add_i32 s8, s8, 0x2400
	v_mov_b32_e32 v4, s9
	v_mov_b32_e32 v5, 1
	global_atomic_add v6, v4, v5, s[6:7] sc0
	buffer_inv sc1
	s_waitcnt vmcnt(0) lgkmcnt(0)
	v_readfirstlane_b32 s10, v6
	v_readfirstlane_b32 s11, v2
	v_readfirstlane_b32 s16, v3
	s_add_i32 s10, s10, 1
	s_mul_i32 s11, s11, 5
	s_cmp_lg_u32 s10, s11
	s_cbranch_scc1 .Lxb_nl_4
	v_mov_b32_e32 v4, 0x3400
	global_atomic_add v6, v4, v5, s[6:7] sc0
	s_waitcnt vmcnt(0)
	v_readfirstlane_b32 s10, v6
	s_add_i32 s10, s10, 1
	s_mul_i32 s16, s16, 5
	s_cmp_lg_u32 s10, s16
	s_cbranch_scc1 .Lxb_nl_4
	v_mov_b32_e32 v4, 0x2400
	global_atomic_add v4, v5, s[6:7]
	global_atomic_add v4, v5, s[6:7] offset:256
	global_atomic_add v4, v5, s[6:7] offset:512
	global_atomic_add v4, v5, s[6:7] offset:768
	global_atomic_add v4, v5, s[6:7] offset:1024
	global_atomic_add v4, v5, s[6:7] offset:1280
	global_atomic_add v4, v5, s[6:7] offset:1536
	global_atomic_add v4, v5, s[6:7] offset:1792
	global_atomic_add v4, v5, s[6:7] offset:2048
	global_atomic_add v4, v5, s[6:7] offset:2304
	global_atomic_add v4, v5, s[6:7] offset:2560
	global_atomic_add v4, v5, s[6:7] offset:2816
	global_atomic_add v4, v5, s[6:7] offset:3072
	global_atomic_add v4, v5, s[6:7] offset:3328
	global_atomic_add v4, v5, s[6:7] offset:3584
	global_atomic_add v4, v5, s[6:7] offset:3840
	s_branch .Lxb_done_4
